# L2 residency in the mixer, step 2: attention output stores and the read-once Q fragment loads also non-temporal (timing-only)
# baseline (speedup 1.0000x reference)
.LBB0_205:
	v_or_b32_e32 v0, s66, v148
	v_mul_i32_i24_e32 v14, 0x1800, v0
	ds_bpermute_b32 v0, v153, v143
	s_add_u32 s4, s20, s34
	s_addc_u32 s5, s21, s35
	v_ashrrev_i32_e32 v15, 31, v14
	v_lshl_add_u64 v[14:15], s[4:5], 0, v[14:15]
	s_lshl_b32 s84, s65, 7
	v_lshl_add_u64 v[14:15], v[14:15], 0, s[84:85]
	v_mov_b32_e32 v141, v1
	v_lshl_add_u64 v[14:15], v[14:15], 0, v[140:141]
	s_waitcnt lgkmcnt(0)
	v_add_f32_e32 v0, v143, v0
	global_load_dwordx4 v[64:67], v[14:15], off nt
	global_load_dwordx4 v[68:71], v[14:15], off offset:32 nt
	global_load_dwordx4 v[72:75], v[14:15], off offset:64 nt
	global_load_dwordx4 v[76:79], v[14:15], off offset:96 nt
	v_div_scale_f32 v14, s[4:5], v0, v0, 1.0
	v_rcp_f32_e32 v15, v14
	s_lshl_b64 s[4:5], s[28:29], 22
	v_ashrrev_i32_e32 v145, 31, v144
	s_add_u32 s4, s22, s4
	v_fma_f32 v48, -v14, v15, 1.0
	v_fmac_f32_e32 v15, v48, v15
	v_div_scale_f32 v48, vcc, 1.0, v0, 1.0
	v_mul_f32_e32 v49, v48, v15
	v_fma_f32 v50, -v14, v49, v48
	v_fmac_f32_e32 v49, v50, v15
	v_fma_f32 v14, -v14, v49, v48
	v_div_fmas_f32 v14, v14, v15, v49
	v_div_fixup_f32 v0, v14, v0, 1.0
	v_pk_mul_f32 v[14:15], v[42:43], v[0:1] op_sel_hi:[1,0]
	v_pk_mul_f32 v[50:51], v[26:27], v[0:1] op_sel_hi:[1,0]
	v_pk_mul_f32 v[26:27], v[14:15], v[14:15]
	v_pk_mul_f32 v[42:43], v[44:45], v[0:1] op_sel_hi:[1,0]
	v_pk_fma_f32 v[52:53], v[50:51], v[50:51], v[26:27]
	v_pk_mul_f32 v[48:49], v[28:29], v[0:1] op_sel_hi:[1,0]
	v_pk_mul_f32 v[26:27], v[42:43], v[42:43]
	v_pk_mul_f32 v[44:45], v[30:31], v[0:1] op_sel_hi:[1,0]
	v_pk_mul_f32 v[30:31], v[46:47], v[0:1] op_sel_hi:[1,0]
	v_pk_fma_f32 v[54:55], v[48:49], v[48:49], v[26:27]
	v_pk_mul_f32 v[26:27], v[30:31], v[30:31]
	s_addc_u32 s5, s23, s5
	v_pk_fma_f32 v[56:57], v[44:45], v[44:45], v[26:27]
	v_lshlrev_b64 v[26:27], 11, v[144:145]
	v_lshl_add_u64 v[26:27], s[4:5], 0, v[26:27]
	s_lshl_b32 s84, s19, 7
	v_lshl_add_u64 v[62:63], v[26:27], 0, s[84:85]
	s_lshl_b32 s84, s19, 8
	v_lshl_add_u64 v[46:47], v[138:139], 0, s[84:85]
	global_load_dwordx4 v[26:29], v[46:47], off
	global_load_dwordx4 v[58:61], v[46:47], off offset:128
	v_pk_mul_f32 v[168:169], v[18:19], v[0:1] op_sel_hi:[1,0]
	v_pk_mul_f32 v[172:173], v[16:17], v[0:1] op_sel_hi:[1,0]
	global_load_dwordx4 v[16:19], v[46:47], off offset:32
	global_load_dwordx4 v[162:165], v[46:47], off offset:160
	v_pk_mul_f32 v[166:167], v[32:33], v[0:1] op_sel_hi:[1,0]
	v_pk_mul_f32 v[144:145], v[34:35], v[0:1] op_sel_hi:[1,0]
	v_pk_mul_f32 v[32:33], v[166:167], v[166:167]
	v_mov_b32_e32 v143, v1
	v_pk_mul_f32 v[34:35], v[144:145], v[144:145]
	v_pk_fma_f32 v[174:175], v[172:173], v[172:173], v[32:33]
	v_lshl_add_u64 v[32:33], v[62:63], 0, v[142:143]
	v_pk_mul_f32 v[38:39], v[38:39], v[0:1] op_sel_hi:[1,0]
	v_pk_mul_f32 v[62:63], v[36:37], v[0:1] op_sel_hi:[1,0]
	v_pk_fma_f32 v[170:171], v[168:169], v[168:169], v[34:35]
	v_pk_mul_f32 v[34:35], v[62:63], v[62:63]
	v_pk_mul_f32 v[176:177], v[22:23], v[0:1] op_sel_hi:[1,0]
	v_pk_mul_f32 v[22:23], v[38:39], v[38:39]
	v_pk_mul_f32 v[180:181], v[20:21], v[0:1] op_sel_hi:[1,0]
	v_pk_fma_f32 v[178:179], v[176:177], v[176:177], v[22:23]
	v_pk_fma_f32 v[182:183], v[180:181], v[180:181], v[34:35]
	global_load_dwordx4 v[20:23], v[46:47], off offset:64
	global_load_dwordx4 v[34:37], v[46:47], off offset:192
	v_pk_mul_f32 v[40:41], v[40:41], v[0:1] op_sel_hi:[1,0]
	v_pk_mul_f32 v[24:25], v[24:25], v[0:1] op_sel_hi:[1,0]
	v_add_f32_e32 v0, v174, v175
	v_add_f32_e32 v0, v170, v0
	v_add_f32_e32 v0, v171, v0
	v_add_f32_e32 v0, v182, v0
	v_add_f32_e32 v0, v183, v0
	v_pk_mul_f32 v[184:185], v[40:41], v[40:41]
	v_add_f32_e32 v0, v178, v0
	v_pk_fma_f32 v[184:185], v[24:25], v[24:25], v[184:185]
	v_add_f32_e32 v0, v179, v0
	v_add_f32_e32 v0, v184, v0
	v_add_f32_e32 v0, v185, v0
	v_add_f32_e32 v0, v52, v0
	v_add_f32_e32 v0, v53, v0
	v_add_f32_e32 v0, v54, v0
	v_add_f32_e32 v0, v55, v0
	v_add_f32_e32 v0, v56, v0
	v_add_f32_e32 v0, v57, v0
	ds_bpermute_b32 v52, v153, v0
	s_waitcnt lgkmcnt(0)
	v_add_f32_e32 v0, v0, v52
	v_fmamk_f32 v0, v0, 0x3c800000, v212
	v_cmp_gt_f32_e32 vcc, s10, v0
	v_mul_f32_e32 v52, 0x4b800000, v0
	s_nop 0
	v_cndmask_b32_e32 v0, v0, v52, vcc
	v_rsq_f32_e32 v0, v0
	s_nop 0
	v_mul_f32_e32 v52, 0x45800000, v0
	v_cndmask_b32_e32 v0, v0, v52, vcc
	v_pk_mul_f32 v[52:53], v[172:173], v[0:1] op_sel_hi:[1,0]
	v_pk_mul_f32 v[14:15], v[14:15], v[0:1] op_sel_hi:[1,0]
	s_andn2_b64 vcc, exec, s[26:27]
	s_waitcnt vmcnt(5)
	v_pk_mul_f32 v[26:27], v[26:27], v[52:53]
	v_pk_mul_f32 v[52:53], v[168:169], v[0:1] op_sel_hi:[1,0]
	v_cvt_pk_bf16_f32 v26, v26, v27
	v_pk_mul_f32 v[28:29], v[28:29], v[52:53]
	v_pk_mul_f32 v[52:53], v[144:145], v[0:1] op_sel_hi:[1,0]
	v_cvt_pk_bf16_f32 v27, v28, v29
	v_pk_mul_f32 v[28:29], v[166:167], v[0:1] op_sel_hi:[1,0]
	s_waitcnt vmcnt(4)
	v_pk_mul_f32 v[52:53], v[60:61], v[52:53]
	v_pk_mul_f32 v[28:29], v[58:59], v[28:29]
	s_waitcnt vmcnt(0)
	v_pk_mul_f32 v[14:15], v[36:37], v[14:15]
	v_cvt_pk_bf16_f32 v28, v28, v29
	v_cvt_pk_bf16_f32 v29, v52, v53
	global_store_dwordx2 v[32:33], v[26:27], off nt
	global_store_dwordx2 v[32:33], v[28:29], off offset:64 nt
	v_pk_mul_f32 v[26:27], v[180:181], v[0:1] op_sel_hi:[1,0]
	s_nop 0
	v_pk_mul_f32 v[16:17], v[16:17], v[26:27]
	v_pk_mul_f32 v[26:27], v[176:177], v[0:1] op_sel_hi:[1,0]
	v_cvt_pk_bf16_f32 v16, v16, v17
	v_pk_mul_f32 v[18:19], v[18:19], v[26:27]
	v_pk_mul_f32 v[26:27], v[38:39], v[0:1] op_sel_hi:[1,0]
	v_cvt_pk_bf16_f32 v17, v18, v19
	v_pk_mul_f32 v[18:19], v[62:63], v[0:1] op_sel_hi:[1,0]
	v_pk_mul_f32 v[26:27], v[164:165], v[26:27]
	v_pk_mul_f32 v[18:19], v[162:163], v[18:19]
	s_nop 0
	v_cvt_pk_bf16_f32 v18, v18, v19
	v_cvt_pk_bf16_f32 v19, v26, v27
	global_store_dwordx2 v[32:33], v[16:17], off offset:16 nt
	global_store_dwordx2 v[32:33], v[18:19], off offset:80 nt
	v_pk_mul_f32 v[16:17], v[24:25], v[0:1] op_sel_hi:[1,0]
	v_pk_mul_f32 v[18:19], v[50:51], v[0:1] op_sel_hi:[1,0]
	v_pk_mul_f32 v[16:17], v[20:21], v[16:17]
	v_pk_mul_f32 v[18:19], v[22:23], v[18:19]
	v_cvt_pk_bf16_f32 v16, v16, v17
	v_cvt_pk_bf16_f32 v17, v18, v19
	v_pk_mul_f32 v[18:19], v[40:41], v[0:1] op_sel_hi:[1,0]
	v_pk_mul_f32 v[22:23], v[48:49], v[0:1] op_sel_hi:[1,0]
	v_pk_mul_f32 v[18:19], v[34:35], v[18:19]
	s_nop 0
	v_cvt_pk_bf16_f32 v18, v18, v19
	v_cvt_pk_bf16_f32 v19, v14, v15
	global_store_dwordx2 v[32:33], v[16:17], off offset:32 nt
	global_store_dwordx2 v[32:33], v[18:19], off offset:96 nt
	global_load_dwordx4 v[14:17], v[46:47], off offset:96
	s_nop 0
	global_load_dwordx4 v[18:21], v[46:47], off offset:224
	s_waitcnt vmcnt(1)
	v_pk_mul_f32 v[14:15], v[14:15], v[22:23]
	v_pk_mul_f32 v[22:23], v[44:45], v[0:1] op_sel_hi:[1,0]
	v_cvt_pk_bf16_f32 v14, v14, v15
	v_pk_mul_f32 v[16:17], v[16:17], v[22:23]
	s_nop 0
	v_cvt_pk_bf16_f32 v15, v16, v17
	v_pk_mul_f32 v[16:17], v[42:43], v[0:1] op_sel_hi:[1,0]
	s_waitcnt vmcnt(0)
	v_pk_mul_f32 v[16:17], v[18:19], v[16:17]
	v_pk_mul_f32 v[18:19], v[30:31], v[0:1] op_sel_hi:[1,0]
	v_cvt_pk_bf16_f32 v16, v16, v17
	v_pk_mul_f32 v[18:19], v[20:21], v[18:19]
	s_nop 0
	v_cvt_pk_bf16_f32 v17, v18, v19
	global_store_dwordx2 v[32:33], v[14:15], off offset:48 nt
	global_store_dwordx2 v[32:33], v[16:17], off offset:112 nt
	s_cbranch_vccnz .LBB0_207
	v_mov_b64_e32 v[82:83], v[8:9]
	v_mov_b64_e32 v[104:105], v[128:129]
	v_mov_b64_e32 v[96:97], v[120:121]
	v_mov_b64_e32 v[88:89], v[112:113]
	v_mov_b64_e32 v[86:87], v[4:5]
	v_mov_b64_e32 v[94:95], v[12:13]
	v_mov_b64_e32 v[100:101], v[116:117]
	v_mov_b64_e32 v[108:109], v[124:125]
	v_mov_b64_e32 v[80:81], v[6:7]
	v_mov_b64_e32 v[106:107], v[130:131]
	v_mov_b64_e32 v[98:99], v[122:123]
	v_mov_b64_e32 v[90:91], v[114:115]
	v_mov_b64_e32 v[84:85], v[2:3]
	v_mov_b64_e32 v[92:93], v[10:11]
	v_mov_b64_e32 v[102:103], v[118:119]
	v_mov_b64_e32 v[110:111], v[126:127]
